# up-GEMM staging: each wave loads both 64-byte halves of the same 16 rows (pieces 2w,2w+1) so the halves of a cache line are requested back to back
# baseline (speedup 1.0000x reference)
; __device__ __forceinline__ int lau_v(int x) { asm volatile("" : "+v"(x)); return x; }
; __device__ __forceinline__ int lane_id() { int l; asm volatile("v_mbcnt_lo_u32_b32 %0, -1, 0\n\tv_mbcnt_hi_u32_b32 %0, -1, %0" : "=v"(l)); return l; }
;     __device__ __forceinline__ size_t aoff(const Unit& u) const { return (size_t)u.pm * bm * lda * 2; }
;     __device__ __forceinline__ size_t boff(const Unit& u) const { return (size_t)u.pn * BM * ldb * 2; }
;     __device__ __forceinline__ size_t aoff(const Unit& u) const { return ((size_t)u.pm * BM * lda + (size_t)u.pn * akoff) * 2; }
;     __device__ __forceinline__ size_t boff(const Unit& u) const { return (size_t)u.pn * BM * ldb * 2; }
;     __device__ __forceinline__ size_t aoff(const Unit& u) const { return ((size_t)u.pm * BM * lda + (size_t)(u.pn >> 1) * akoff) * 2; }
;     __device__ __forceinline__ size_t boff(const Unit& u) const { return (size_t)u.pn * BM * ldb * 2; }
;     const int lane = lau_v(lane_id()), tid = wid * 64 + lane, wr = wid >> 2, wc = wid & 3, fr = lane & 15, fq = lane >> 4;
;     const int K = g.K, nt = K / BK;
;     unsigned voffA[2], voffB[2];
; #pragma unroll
;     for (int i = 0; i < 2; ++i) { int R, C; stage_rc(tid * 16 + i * 8192, R, C); const int Rb = Epi::PERM ? ((R & ~31) + perm32(R & 31)) : R;
;         voffA[i] = (unsigned)(R * g.lda + C) * 2u; voffB[i] = (unsigned)(Rb * g.ldb + C) * 2u; }
;     const size_t kstep = (size_t)(BK * 2);
;     const size_t hstepA = (size_t)(32 * NM) * g.lda * 2, hstepB = (size_t)HALF * g.ldb * 2;
;     const unsigned ldsw = (unsigned)wid * 1024u;
;     const int aoff = lds_byte(wr * (16 * NM) + fr, fq * 8), boff = lds_byte(wc * 32 + fr, fq * 8);
.LBB0_1767:
	v_readlane_b32 s2, v255, 51
	s_waitcnt lgkmcnt(0)
	s_add_u32 s4, s16, s2
	v_readlane_b32 s2, v255, 50
	s_addc_u32 s5, s17, s2
	v_writelane_b32 v255, s4, 37
	s_mul_i32 s3, s22, 0x2c0000
	v_lshl_add_u64 v[6:7], v[6:7], 0, s[66:67]
	v_writelane_b32 v255, s5, 38
	s_waitcnt vmcnt(2)
	s_barrier
	v_readlane_b32 s2, v255, 52
	s_add_u32 s18, s18, s2
	s_addc_u32 s19, s19, s97
	v_writelane_b32 v255, s97, 44
	s_mul_hi_u32 s2, s22, 0x2c0000
	s_add_u32 s81, s20, s3
	s_addc_u32 s92, s21, s2
	s_add_i32 s94, s55, 0x18000
	v_readlane_b32 s4, v255, 30
	v_readlane_b32 s9, v255, 31
	s_add_i32 s51, s94, s4
	s_lshl_b32 s93, s9, 6
	s_mov_b32 m0, s51
	s_add_i32 s95, s51, 0x2000
	s_add_i32 s58, s73, 0x8000
	s_add_i32 s59, s73, 0xa000
	global_load_lds_dwordx4 v[6:7], off
	v_lshl_add_u64 v[4:5], v[4:5], 0, s[66:67]
	s_mov_b32 m0, s95
	s_add_u32 s2, s14, 0x80080
	global_load_lds_dwordx4 v[4:5], off
	v_lshl_add_u64 v[2:3], v[2:3], 0, s[66:67]
	s_mov_b32 m0, s58
	s_addc_u32 s3, s15, 0
	s_add_i32 s62, s55, 0x1c000
	global_load_lds_dwordx4 v[2:3], off
	v_lshl_add_u64 v[2:3], v[8:9], 0, s[66:67]
	s_mov_b32 m0, s59
	s_add_i32 s50, s62, s4
	global_load_lds_dwordx4 v[2:3], off
	v_lshl_add_u64 v[2:3], s[2:3], 0, v[180:181]
	s_mov_b32 m0, s50
	s_add_i32 s49, s50, 0x2000
	global_load_lds_dwordx4 v[2:3], off
	v_lshl_add_u64 v[2:3], s[2:3], 0, v[184:185]
	s_mov_b32 m0, s49
	v_lshlrev_b32_e32 v5, 6, v0
	global_load_lds_dwordx4 v[2:3], off
	v_and_b32_e32 v2, 48, v0
	s_movk_i32 s2, 0x3c0
	v_writelane_b32 v255, s96, 36
	v_and_or_b32 v2, v5, s2, v2
	v_readlane_b32 s2, v255, 27
	s_cmp_gt_i32 s2, 3
	s_cselect_b64 s[20:21], -1, 0
	s_cmp_eq_u32 s2, 4
	s_cselect_b64 s[4:5], -1, 0
	v_writelane_b32 v255, s4, 20
	s_add_i32 s38, s55, 0x22000
	v_and_b32_e32 v3, 0xfffffc00, v16
	v_writelane_b32 v255, s5, 21
	s_add_i32 s4, s55, 0x24000
	s_lshl_b32 s5, s2, 1
	s_cmp_lt_u32 s2, 4
	s_cselect_b64 s[24:25], -1, 0
	s_cmp_gt_u32 s2, 3
	v_readlane_b32 s11, v255, 33
	s_cselect_b64 s[26:27], -1, 0
	s_lshl_b32 s2, s9, 5
	s_lshl_b32 s3, s11, 3
	v_lshl_add_u32 v4, s9, 13, v3
	v_add_u32_e32 v3, s96, v3
	s_or_b32 s96, s2, s3
	s_lshl_b32 s2, s9, 11
	s_lshl_b32 s9, s9, 8
	s_add_i32 s82, s4, s9
	v_readlane_b32 s9, v255, 32
	s_lshl_b32 s9, s9, 2
	s_add_i32 s54, s96, 64
	s_lshl_b32 s3, s11, 9
	s_ashr_i32 s89, s53, 31
	s_ashr_i32 s52, s46, 31
	s_add_i32 s97, s38, s9
	s_add_u32 s9, s6, s41
	s_addc_u32 s11, s7, s40
	v_lshlrev_b32_e32 v0, 2, v0
	s_add_u32 s9, s9, 0x2d7c8000
	v_and_b32_e32 v0, 32, v0
	v_writelane_b32 v255, s9, 39
	s_addc_u32 s9, s11, 0
	v_bitop3_b32 v4, v2, v4, v0 bitop3:0xde
	v_bitop3_b32 v208, v2, v3, v0 bitop3:0xde
	s_add_u32 s65, s6, 0x2daaa000
	v_lshlrev_b32_e32 v0, 15, v10
	s_addc_u32 s16, s7, 0
	s_add_i32 s17, s55, 0x20000
	v_and_b32_e32 v0, 0xffff0000, v0
	s_add_u32 s28, s30, 0x13870000
	v_lshl_add_u32 v0, v11, 12, v0
	v_and_b32_e32 v2, 1, v10
	s_addc_u32 s29, s31, 0
	s_lshl_b32 s91, s22, 6
	v_lshl_or_b32 v0, v2, 6, v0
	s_add_u32 s30, s30, 0xe8f0000
	v_lshl_add_u32 v186, v12, 1, v0
	v_lshlrev_b32_e32 v0, 15, v13
	s_addc_u32 s31, s31, 0
	s_lshl_b32 s56, s22, 4
	v_and_b32_e32 v0, 0xffff0000, v0
	s_waitcnt vmcnt(6)
	s_add_u32 s34, s6, 0x5930a000
	v_lshl_add_u32 v0, v14, 12, v0
	v_and_b32_e32 v2, 1, v13
	s_addc_u32 s35, s7, 0
	s_add_i32 s57, s17, s2
	v_lshl_or_b32 v0, v2, 6, v0
	v_writelane_b32 v255, s9, 40
	s_add_i32 s57, s57, s3
	v_mov_b32_e32 v187, v1
	v_lshl_add_u32 v188, v15, 1, v0
	v_mov_b32_e32 v189, v1
	s_mov_b32 s79, 0
	v_add_u32_e32 v209, s55, v4
	s_mov_b32 s78, 0
	v_readlane_b32 s2, v255, 27
	v_mbcnt_lo_u32_b32 v218, -1, 0
	v_mbcnt_hi_u32_b32 v218, -1, v218
	s_nop 3
	s_lshl_b32 s3, s2, 4
	v_lshrrev_b32_e32 v219, 2, v218
	v_add_u32_e32 v220, s3, v219
	v_lshrrev_b32_e32 v221, 5, v218
	v_lshlrev_b32_e32 v221, 1, v221
	v_and_b32_e32 v222, 3, v218
	v_xor_b32_e32 v222, v222, v221
	v_lshlrev_b32_e32 v222, 4, v222
	v_lshl_add_u32 v178, v220, 12, v222
	v_add_u32_e32 v182, 64, v178
	v_mov_b32_e32 v186, v178
	v_mov_b32_e32 v188, v182
	s_lshr_b32 s3, s2, 1
	s_lshl_b32 s3, s3, 5
	s_and_b32 s100, s2, 1
	s_lshl_b32 s100, s100, 2
	s_add_i32 s3, s3, s100
	v_lshrrev_b32_e32 v223, 4, v218
	v_and_b32_e32 v224, 3, v219
	v_lshl_add_u32 v223, v223, 3, v224
	v_add_u32_e32 v223, s3, v223
	v_lshl_add_u32 v180, v223, 12, v222
	v_add_u32_e32 v184, 64, v180
	s_lshl_b32 s3, s2, 11
	s_add_i32 s73, s55, s3
	s_add_i32 s74, s73, 0x400
	s_add_i32 s75, s73, 0x4000
	s_add_i32 s80, s75, 0x400
	s_add_i32 s58, s73, 0x8000
	s_add_i32 s59, s58, 0x400
	s_add_i32 s68, s64, s3
	s_add_i32 s69, s68, 0x400
	s_add_i32 s71, s70, s3
	s_add_i32 s72, s71, 0x400
	s_add_i32 s51, s94, s3
	s_add_i32 s95, s51, 0x400
	s_add_i32 s50, s62, s3
	s_add_i32 s49, s50, 0x400
	s_barrier
	s_branch .LBB0_1770

; #define PG8_STAGE(bufoff, gbase, voff) do { _Pragma("unroll") for (int _i = 0; _i < 2; ++_i) \
;         __builtin_amdgcn_global_load_lds((const unsigned*)((const char*)(gbase) + (voff)[_i]), (LAS unsigned*)(lds + (bufoff) + ldsw + _i * 8192), 16, 0, 0); } while (0)
; #define PG8_LDA(dst, b, h) do { _Pragma("unroll") for (int m = 0; m < NM; ++m) _Pragma("unroll") for (int k = 0; k < 2; ++k) dst[m][k] = *(const LAS bf16x8*)(lds + PG8_SA(b, h) + aoff + m * 2048 + k * 1024); } while (0)
; #define PG8_LDB(dst, b, h) do { _Pragma("unroll") for (int n = 0; n < 2; ++n) _Pragma("unroll") for (int k = 0; k < 2; ++k) dst[n][k] = *(const LAS bf16x8*)(lds + PG8_SB(b, h) + boff + n * 2048 + k * 1024); } while (0)
; #define PG8_MMA(ai, bj, At, Bt) do { __builtin_amdgcn_s_setprio(1); _Pragma("unroll") for (int m = 0; m < NM; ++m) _Pragma("unroll") for (int n = 0; n < 2; ++n) _Pragma("unroll") for (int k = 0; k < 2; ++k) \
;         acc[ai][bj][m][n] = __builtin_amdgcn_mfma_f32_16x16x32_bf16(Bt[n][k], At[m][k], acc[ai][bj][m][n], 0, 0, 0); __builtin_amdgcn_s_setprio(0); } while (0)
; #define PG8_WAIT_V(n) asm volatile("s_waitcnt vmcnt(" #n ")" ::: "memory")
; #define PG8_WAIT_L(n) asm volatile("s_waitcnt lgkmcnt(" #n ")" ::: "memory")
; #define PG8_BAR __builtin_amdgcn_s_barrier()
; #define PG8_SCHED __builtin_amdgcn_sched_barrier(0)
;     ...
;         for (int t = 0; t < nt; t += 2) {
;             const bool last = (t == nt - 2);
;             const char* a1 = cA + (size_t)(t + 1) * kstep;
;             const char* a2 = last ? nA : cA + (size_t)(t + 2) * kstep; const char* b2 = last ? nB : cB + (size_t)(t + 2) * kstep;
;             const char* a3 = a2 + kstep; const char* b3 = b2 + kstep;
;             if constexpr (SP2) {
;             PG8_LDB(B0, 0, 0); PG8_LDB(B1, 0, 1); PG8_SCHED; PG8_LDA(At, 0, 0); PG8_STAGE(PG8_SA(1, 1), a1 + hstepA, voffA);
;             PG8_WAIT_V(8); PG8_WAIT_L(0); PG8_BAR; PG8_MMA(0, 0, At, B0); PG8_MMA(0, 1, At, B1); PG8_BAR; PG8_SCHED;
;             PG8_LDA(At, 0, 1); PG8_STAGE(PG8_SB(0, 0), b2, voffB); PG8_STAGE(PG8_SB(0, 1), b2 + hstepB, voffB); PG8_STAGE(PG8_SA(0, 0), a2, voffA);
;             PG8_WAIT_V(8); PG8_WAIT_L(0); PG8_BAR; PG8_MMA(1, 0, At, B0); PG8_MMA(1, 1, At, B1); PG8_BAR; PG8_SCHED;
.LBB0_1783:
	v_add_u32_e32 v0, s64, v208
	ds_read_b128 v[130:133], v0
	ds_read_b128 v[134:137], v0 offset:1024
	ds_read_b128 v[138:141], v0 offset:2048
	ds_read_b128 v[142:145], v0 offset:3072
	v_add_u32_e32 v0, s70, v208
	ds_read_b128 v[146:149], v0
	ds_read_b128 v[150:153], v0 offset:1024
	ds_read_b128 v[154:157], v0 offset:2048
	ds_read_b128 v[158:161], v0 offset:3072
	s_add_u32 s14, s12, 0xfff80080
	s_addc_u32 s15, s13, -1
	s_cmp_eq_u32 vcc_lo, 28
	s_cselect_b32 s47, s2, s15
	s_cselect_b32 s46, s3, s14
	s_cselect_b32 s15, s9, s41
	s_cselect_b32 s14, s11, s37
	s_add_i32 m0, s73, 0xc000
	ds_read_b128 v[162:165], v209
	ds_read_b128 v[166:169], v209 offset:1024
	ds_read_b128 v[170:173], v209 offset:2048
	ds_read_b128 v[174:177], v209 offset:3072
	ds_read_b128 v[190:193], v209 offset:4096
	ds_read_b128 v[194:197], v209 offset:5120
	ds_read_b128 v[198:201], v209 offset:6144
	ds_read_b128 v[202:205], v209 offset:7168
	global_load_lds_dwordx4 v186, s[12:13]
	s_add_i32 m0, s73, 0xc400
	s_nop 0
	global_load_lds_dwordx4 v188, s[12:13]
	s_waitcnt vmcnt(8)
	s_waitcnt lgkmcnt(0)
	s_barrier
	s_setprio 1
	s_waitcnt lgkmcnt(0)
	v_mfma_f32_16x16x32_bf16 v[126:129], v[130:133], v[162:165], v[126:129]
	v_mfma_f32_16x16x32_bf16 v[94:97], v[138:141], v[162:165], v[94:97]
	v_mfma_f32_16x16x32_bf16 v[110:113], v[130:133], v[170:173], v[110:113]
	v_mfma_f32_16x16x32_bf16 v[70:73], v[138:141], v[170:173], v[70:73]
	v_mfma_f32_16x16x32_bf16 v[106:109], v[130:133], v[190:193], v[106:109]
	v_mfma_f32_16x16x32_bf16 v[66:69], v[138:141], v[190:193], v[66:69]
	v_mfma_f32_16x16x32_bf16 v[118:121], v[130:133], v[198:201], v[118:121]
	v_mfma_f32_16x16x32_bf16 v[86:89], v[138:141], v[198:201], v[86:89]
	v_mfma_f32_16x16x32_bf16 v[126:129], v[134:137], v[166:169], v[126:129]
	v_mfma_f32_16x16x32_bf16 v[94:97], v[142:145], v[166:169], v[94:97]
	v_mfma_f32_16x16x32_bf16 v[110:113], v[134:137], v[174:177], v[110:113]
	v_mfma_f32_16x16x32_bf16 v[70:73], v[142:145], v[174:177], v[70:73]
	v_mfma_f32_16x16x32_bf16 v[106:109], v[134:137], v[194:197], v[106:109]
	v_mfma_f32_16x16x32_bf16 v[66:69], v[142:145], v[194:197], v[66:69]
	v_mfma_f32_16x16x32_bf16 v[118:121], v[134:137], v[202:205], v[118:121]
	v_mfma_f32_16x16x32_bf16 v[86:89], v[142:145], v[202:205], v[86:89]
	s_setprio 0
	s_setprio 1
	v_mfma_f32_16x16x32_bf16 v[122:125], v[146:149], v[162:165], v[122:125]
	v_mfma_f32_16x16x32_bf16 v[90:93], v[154:157], v[162:165], v[90:93]
	v_mfma_f32_16x16x32_bf16 v[102:105], v[146:149], v[170:173], v[102:105]
	v_mfma_f32_16x16x32_bf16 v[62:65], v[154:157], v[170:173], v[62:65]
	v_mfma_f32_16x16x32_bf16 v[98:101], v[146:149], v[190:193], v[98:101]
	v_mfma_f32_16x16x32_bf16 v[58:61], v[154:157], v[190:193], v[58:61]
	v_mfma_f32_16x16x32_bf16 v[114:117], v[146:149], v[198:201], v[114:117]
	v_mfma_f32_16x16x32_bf16 v[82:85], v[154:157], v[198:201], v[82:85]
	v_mfma_f32_16x16x32_bf16 v[122:125], v[150:153], v[166:169], v[122:125]
	v_mfma_f32_16x16x32_bf16 v[90:93], v[158:161], v[166:169], v[90:93]
	v_mfma_f32_16x16x32_bf16 v[102:105], v[150:153], v[174:177], v[102:105]
	v_mfma_f32_16x16x32_bf16 v[62:65], v[158:161], v[174:177], v[62:65]
	v_mfma_f32_16x16x32_bf16 v[98:101], v[150:153], v[194:197], v[98:101]
	v_mfma_f32_16x16x32_bf16 v[58:61], v[158:161], v[194:197], v[58:61]
	v_mfma_f32_16x16x32_bf16 v[114:117], v[150:153], v[202:205], v[114:117]
	v_mfma_f32_16x16x32_bf16 v[82:85], v[158:161], v[202:205], v[82:85]
	s_setprio 0
	s_barrier
	s_mov_b32 m0, s68
	s_add_u32 s22, s14, 0x80000
	ds_read_b128 v[162:165], v209 offset:16384
	ds_read_b128 v[166:169], v209 offset:17408
	ds_read_b128 v[170:173], v209 offset:18432
	ds_read_b128 v[174:177], v209 offset:19456
	ds_read_b128 v[190:193], v209 offset:20480
	ds_read_b128 v[194:197], v209 offset:21504
	ds_read_b128 v[198:201], v209 offset:22528
	ds_read_b128 v[202:205], v209 offset:23552
	global_load_lds_dwordx4 v180, s[14:15]
	s_mov_b32 m0, s69
	s_addc_u32 s23, s15, 0
	global_load_lds_dwordx4 v184, s[14:15]
	s_mov_b32 m0, s71
	s_nop 0
	global_load_lds_dwordx4 v180, s[22:23]
	s_mov_b32 m0, s72
	s_nop 0
	global_load_lds_dwordx4 v184, s[22:23]
	s_mov_b32 m0, s73
	s_nop 0
	global_load_lds_dwordx4 v178, s[46:47]
	s_mov_b32 m0, s74
	s_nop 0
	global_load_lds_dwordx4 v182, s[46:47]
	s_waitcnt vmcnt(8)
	s_waitcnt lgkmcnt(0)
	s_barrier
	s_setprio 1
	s_waitcnt lgkmcnt(0)
	v_mfma_f32_16x16x32_bf16 v[46:49], v[130:133], v[162:165], v[46:49]
	v_mfma_f32_16x16x32_bf16 v[22:25], v[138:141], v[162:165], v[22:25]
	v_mfma_f32_16x16x32_bf16 v[42:45], v[130:133], v[170:173], v[42:45]
	v_mfma_f32_16x16x32_bf16 v[18:21], v[138:141], v[170:173], v[18:21]
	v_mfma_f32_16x16x32_bf16 v[38:41], v[130:133], v[190:193], v[38:41]
	v_mfma_f32_16x16x32_bf16 v[14:17], v[138:141], v[190:193], v[14:17]
	v_mfma_f32_16x16x32_bf16 v[78:81], v[130:133], v[198:201], v[78:81]
	v_mfma_f32_16x16x32_bf16 v[54:57], v[138:141], v[198:201], v[54:57]
	v_mfma_f32_16x16x32_bf16 v[46:49], v[134:137], v[166:169], v[46:49]
	v_mfma_f32_16x16x32_bf16 v[22:25], v[142:145], v[166:169], v[22:25]
	v_mfma_f32_16x16x32_bf16 v[42:45], v[134:137], v[174:177], v[42:45]
	v_mfma_f32_16x16x32_bf16 v[18:21], v[142:145], v[174:177], v[18:21]
	v_mfma_f32_16x16x32_bf16 v[38:41], v[134:137], v[194:197], v[38:41]
	v_mfma_f32_16x16x32_bf16 v[14:17], v[142:145], v[194:197], v[14:17]
	v_mfma_f32_16x16x32_bf16 v[78:81], v[134:137], v[202:205], v[78:81]
	v_mfma_f32_16x16x32_bf16 v[54:57], v[142:145], v[202:205], v[54:57]
	s_setprio 0
	s_setprio 1
	v_mfma_f32_16x16x32_bf16 v[34:37], v[146:149], v[162:165], v[34:37]
	v_mfma_f32_16x16x32_bf16 v[10:13], v[154:157], v[162:165], v[10:13]
	v_mfma_f32_16x16x32_bf16 v[30:33], v[146:149], v[170:173], v[30:33]
	v_mfma_f32_16x16x32_bf16 v[6:9], v[154:157], v[170:173], v[6:9]
	v_mfma_f32_16x16x32_bf16 v[26:29], v[146:149], v[190:193], v[26:29]
	v_mfma_f32_16x16x32_bf16 v[2:5], v[154:157], v[190:193], v[2:5]
	v_mfma_f32_16x16x32_bf16 v[74:77], v[146:149], v[198:201], v[74:77]
	v_mfma_f32_16x16x32_bf16 v[50:53], v[154:157], v[198:201], v[50:53]
	v_mfma_f32_16x16x32_bf16 v[34:37], v[150:153], v[166:169], v[34:37]
	v_mfma_f32_16x16x32_bf16 v[10:13], v[158:161], v[166:169], v[10:13]
	v_mfma_f32_16x16x32_bf16 v[30:33], v[150:153], v[174:177], v[30:33]
	v_mfma_f32_16x16x32_bf16 v[6:9], v[158:161], v[174:177], v[6:9]
	v_mfma_f32_16x16x32_bf16 v[26:29], v[150:153], v[194:197], v[26:29]
	v_mfma_f32_16x16x32_bf16 v[2:5], v[158:161], v[194:197], v[2:5]
	v_mfma_f32_16x16x32_bf16 v[74:77], v[150:153], v[202:205], v[74:77]
	v_mfma_f32_16x16x32_bf16 v[50:53], v[158:161], v[202:205], v[50:53]
	s_setprio 0
	s_barrier
; #define PG8_STAGE(bufoff, gbase, voff) do { _Pragma("unroll") for (int _i = 0; _i < 2; ++_i) \
;         __builtin_amdgcn_global_load_lds((const unsigned*)((const char*)(gbase) + (voff)[_i]), (LAS unsigned*)(lds + (bufoff) + ldsw + _i * 8192), 16, 0, 0); } while (0)
; #define PG8_LDA(dst, b, h) do { _Pragma("unroll") for (int m = 0; m < NM; ++m) _Pragma("unroll") for (int k = 0; k < 2; ++k) dst[m][k] = *(const LAS bf16x8*)(lds + PG8_SA(b, h) + aoff + m * 2048 + k * 1024); } while (0)
; #define PG8_LDB(dst, b, h) do { _Pragma("unroll") for (int n = 0; n < 2; ++n) _Pragma("unroll") for (int k = 0; k < 2; ++k) dst[n][k] = *(const LAS bf16x8*)(lds + PG8_SB(b, h) + boff + n * 2048 + k * 1024); } while (0)
; #define PG8_MMA(ai, bj, At, Bt) do { __builtin_amdgcn_s_setprio(1); _Pragma("unroll") for (int m = 0; m < NM; ++m) _Pragma("unroll") for (int n = 0; n < 2; ++n) _Pragma("unroll") for (int k = 0; k < 2; ++k) \
;         acc[ai][bj][m][n] = __builtin_amdgcn_mfma_f32_16x16x32_bf16(Bt[n][k], At[m][k], acc[ai][bj][m][n], 0, 0, 0); __builtin_amdgcn_s_setprio(0); } while (0)
; #define PG8_WAIT_V(n) asm volatile("s_waitcnt vmcnt(" #n ")" ::: "memory")
; #define PG8_WAIT_L(n) asm volatile("s_waitcnt lgkmcnt(" #n ")" ::: "memory")
; #define PG8_BAR __builtin_amdgcn_s_barrier()
; #define PG8_SCHED __builtin_amdgcn_sched_barrier(0)
;     ...
;             PG8_LDB(B0, 1, 0); PG8_LDB(B1, 1, 1); PG8_SCHED; PG8_LDA(At, 1, 0); PG8_STAGE(PG8_SA(0, 1), a2 + hstepA, voffA);
;             PG8_WAIT_V(8); PG8_WAIT_L(0); PG8_BAR; PG8_MMA(0, 0, At, B0); PG8_MMA(0, 1, At, B1); PG8_BAR; PG8_SCHED;
;             PG8_LDA(At, 1, 1); PG8_STAGE(PG8_SB(1, 0), b3, voffB); PG8_STAGE(PG8_SB(1, 1), b3 + hstepB, voffB); PG8_STAGE(PG8_SA(1, 0), a3, voffA);
;             PG8_WAIT_V(8); PG8_WAIT_L(0); PG8_BAR; PG8_MMA(1, 0, At, B0); PG8_MMA(1, 1, At, B1); PG8_BAR; PG8_SCHED;
	v_add_u32_e32 v0, s94, v208
	ds_read_b128 v[130:133], v0
	ds_read_b128 v[134:137], v0 offset:1024
	ds_read_b128 v[138:141], v0 offset:2048
	ds_read_b128 v[142:145], v0 offset:3072
	v_add_u32_e32 v0, s62, v208
	ds_read_b128 v[146:149], v0
	ds_read_b128 v[150:153], v0 offset:1024
	ds_read_b128 v[154:157], v0 offset:2048
	ds_read_b128 v[158:161], v0 offset:3072
	s_add_u32 s22, s46, 0x80000
	s_addc_u32 s23, s47, 0
	s_mov_b32 m0, s75
	ds_read_b128 v[162:165], v209 offset:32768
	ds_read_b128 v[166:169], v209 offset:33792
	ds_read_b128 v[170:173], v209 offset:34816
	ds_read_b128 v[174:177], v209 offset:35840
	ds_read_b128 v[190:193], v209 offset:36864
	ds_read_b128 v[194:197], v209 offset:37888
	ds_read_b128 v[198:201], v209 offset:38912
	ds_read_b128 v[202:205], v209 offset:39936
	global_load_lds_dwordx4 v178, s[22:23]
	s_mov_b32 m0, s80
	s_nop 0
	global_load_lds_dwordx4 v182, s[22:23]
	s_waitcnt vmcnt(8)
	s_waitcnt lgkmcnt(0)
	s_barrier
	s_setprio 1
	s_waitcnt lgkmcnt(0)
	v_mfma_f32_16x16x32_bf16 v[126:129], v[130:133], v[162:165], v[126:129]
	v_mfma_f32_16x16x32_bf16 v[94:97], v[138:141], v[162:165], v[94:97]
	v_mfma_f32_16x16x32_bf16 v[110:113], v[130:133], v[170:173], v[110:113]
	v_mfma_f32_16x16x32_bf16 v[70:73], v[138:141], v[170:173], v[70:73]
	v_mfma_f32_16x16x32_bf16 v[106:109], v[130:133], v[190:193], v[106:109]
	v_mfma_f32_16x16x32_bf16 v[66:69], v[138:141], v[190:193], v[66:69]
	v_mfma_f32_16x16x32_bf16 v[118:121], v[130:133], v[198:201], v[118:121]
	v_mfma_f32_16x16x32_bf16 v[86:89], v[138:141], v[198:201], v[86:89]
	v_mfma_f32_16x16x32_bf16 v[126:129], v[134:137], v[166:169], v[126:129]
	v_mfma_f32_16x16x32_bf16 v[94:97], v[142:145], v[166:169], v[94:97]
	v_mfma_f32_16x16x32_bf16 v[110:113], v[134:137], v[174:177], v[110:113]
	v_mfma_f32_16x16x32_bf16 v[70:73], v[142:145], v[174:177], v[70:73]
	v_mfma_f32_16x16x32_bf16 v[106:109], v[134:137], v[194:197], v[106:109]
	v_mfma_f32_16x16x32_bf16 v[66:69], v[142:145], v[194:197], v[66:69]
	v_mfma_f32_16x16x32_bf16 v[118:121], v[134:137], v[202:205], v[118:121]
	v_mfma_f32_16x16x32_bf16 v[86:89], v[142:145], v[202:205], v[86:89]
	s_setprio 0
	s_setprio 1
	v_mfma_f32_16x16x32_bf16 v[122:125], v[146:149], v[162:165], v[122:125]
	v_mfma_f32_16x16x32_bf16 v[90:93], v[154:157], v[162:165], v[90:93]
	v_mfma_f32_16x16x32_bf16 v[102:105], v[146:149], v[170:173], v[102:105]
	v_mfma_f32_16x16x32_bf16 v[62:65], v[154:157], v[170:173], v[62:65]
	v_mfma_f32_16x16x32_bf16 v[98:101], v[146:149], v[190:193], v[98:101]
	v_mfma_f32_16x16x32_bf16 v[58:61], v[154:157], v[190:193], v[58:61]
	v_mfma_f32_16x16x32_bf16 v[114:117], v[146:149], v[198:201], v[114:117]
	v_mfma_f32_16x16x32_bf16 v[82:85], v[154:157], v[198:201], v[82:85]
	v_mfma_f32_16x16x32_bf16 v[122:125], v[150:153], v[166:169], v[122:125]
	v_mfma_f32_16x16x32_bf16 v[90:93], v[158:161], v[166:169], v[90:93]
	v_mfma_f32_16x16x32_bf16 v[102:105], v[150:153], v[174:177], v[102:105]
	v_mfma_f32_16x16x32_bf16 v[62:65], v[158:161], v[174:177], v[62:65]
	v_mfma_f32_16x16x32_bf16 v[98:101], v[150:153], v[194:197], v[98:101]
	v_mfma_f32_16x16x32_bf16 v[58:61], v[158:161], v[194:197], v[58:61]
	v_mfma_f32_16x16x32_bf16 v[114:117], v[150:153], v[202:205], v[114:117]
	v_mfma_f32_16x16x32_bf16 v[82:85], v[158:161], v[202:205], v[82:85]
	s_setprio 0
	s_barrier
	s_mov_b32 m0, s51
	s_add_u32 s100, s14, s66
	s_addc_u32 s101, s15, s67
	s_add_u32 s14, s14, 0x80080
	s_addc_u32 s15, s15, 0
	ds_read_b128 v[162:165], v209 offset:49152
	ds_read_b128 v[166:169], v209 offset:50176
	ds_read_b128 v[170:173], v209 offset:51200
	ds_read_b128 v[174:177], v209 offset:52224
	ds_read_b128 v[190:193], v209 offset:53248
	ds_read_b128 v[194:197], v209 offset:54272
	ds_read_b128 v[198:201], v209 offset:55296
	ds_read_b128 v[202:205], v209 offset:56320
	global_load_lds_dwordx4 v180, s[100:101]
	s_mov_b32 m0, s95
	s_nop 0
	global_load_lds_dwordx4 v184, s[100:101]
	s_add_u32 s100, s46, s66
	s_addc_u32 s101, s47, s67
	s_mov_b32 m0, s50
	s_nop 0
	global_load_lds_dwordx4 v180, s[14:15]
	s_mov_b32 m0, s49
	s_nop 0
	global_load_lds_dwordx4 v184, s[14:15]
	s_mov_b32 m0, s58
	s_nop 0
	global_load_lds_dwordx4 v178, s[100:101]
	s_mov_b32 m0, s59
	s_nop 0
	global_load_lds_dwordx4 v182, s[100:101]
	s_waitcnt vmcnt(8)
	s_waitcnt lgkmcnt(0)
	s_barrier
	s_setprio 1
	s_waitcnt lgkmcnt(0)
	v_mfma_f32_16x16x32_bf16 v[46:49], v[130:133], v[162:165], v[46:49]
	v_mfma_f32_16x16x32_bf16 v[22:25], v[138:141], v[162:165], v[22:25]
	v_mfma_f32_16x16x32_bf16 v[42:45], v[130:133], v[170:173], v[42:45]
	v_mfma_f32_16x16x32_bf16 v[18:21], v[138:141], v[170:173], v[18:21]
	v_mfma_f32_16x16x32_bf16 v[38:41], v[130:133], v[190:193], v[38:41]
	v_mfma_f32_16x16x32_bf16 v[14:17], v[138:141], v[190:193], v[14:17]
	v_mfma_f32_16x16x32_bf16 v[78:81], v[130:133], v[198:201], v[78:81]
	v_mfma_f32_16x16x32_bf16 v[54:57], v[138:141], v[198:201], v[54:57]
	v_mfma_f32_16x16x32_bf16 v[46:49], v[134:137], v[166:169], v[46:49]
	v_mfma_f32_16x16x32_bf16 v[22:25], v[142:145], v[166:169], v[22:25]
	v_mfma_f32_16x16x32_bf16 v[42:45], v[134:137], v[174:177], v[42:45]
	v_mfma_f32_16x16x32_bf16 v[18:21], v[142:145], v[174:177], v[18:21]
	v_mfma_f32_16x16x32_bf16 v[38:41], v[134:137], v[194:197], v[38:41]
	v_mfma_f32_16x16x32_bf16 v[14:17], v[142:145], v[194:197], v[14:17]
	v_mfma_f32_16x16x32_bf16 v[78:81], v[134:137], v[202:205], v[78:81]
	v_mfma_f32_16x16x32_bf16 v[54:57], v[142:145], v[202:205], v[54:57]
	s_setprio 0
	s_setprio 1
	v_mfma_f32_16x16x32_bf16 v[34:37], v[146:149], v[162:165], v[34:37]
	v_mfma_f32_16x16x32_bf16 v[10:13], v[154:157], v[162:165], v[10:13]
	v_mfma_f32_16x16x32_bf16 v[30:33], v[146:149], v[170:173], v[30:33]
	v_mfma_f32_16x16x32_bf16 v[6:9], v[154:157], v[170:173], v[6:9]
	v_mfma_f32_16x16x32_bf16 v[26:29], v[146:149], v[190:193], v[26:29]
	v_mfma_f32_16x16x32_bf16 v[2:5], v[154:157], v[190:193], v[2:5]
	v_mfma_f32_16x16x32_bf16 v[74:77], v[146:149], v[198:201], v[74:77]
	v_mfma_f32_16x16x32_bf16 v[50:53], v[154:157], v[198:201], v[50:53]
	v_mfma_f32_16x16x32_bf16 v[34:37], v[150:153], v[166:169], v[34:37]
	v_mfma_f32_16x16x32_bf16 v[10:13], v[158:161], v[166:169], v[10:13]
	v_mfma_f32_16x16x32_bf16 v[30:33], v[150:153], v[174:177], v[30:33]
	v_mfma_f32_16x16x32_bf16 v[6:9], v[158:161], v[174:177], v[6:9]
	v_mfma_f32_16x16x32_bf16 v[26:29], v[150:153], v[194:197], v[26:29]
	v_mfma_f32_16x16x32_bf16 v[2:5], v[158:161], v[194:197], v[2:5]
	v_mfma_f32_16x16x32_bf16 v[74:77], v[150:153], v[202:205], v[74:77]
	v_mfma_f32_16x16x32_bf16 v[50:53], v[158:161], v[202:205], v[50:53]
	s_setprio 0
	s_barrier
	s_add_i32 vcc_lo, vcc_lo, 2
	s_add_u32 s12, s12, 0x100
	s_addc_u32 s13, s13, 0
	s_add_u32 s37, s37, 0x100
	s_addc_u32 s41, s41, 0
	s_cmp_gt_u32 vcc_lo, 29
	s_cbranch_scc0 .LBB0_1783
	s_and_b64 vcc, exec, s[24:25]
	s_cbranch_vccz .LBB0_1786
	s_barrier
